# attention: split V-frag ds_read2_b64 into ds_read_b64 pairs, packed b32 V^T LDS writes via DPP, thresholded softmax rescale, drop redundant self-max
# speedup vs baseline: 1.0076x; 1.0076x over previous
; __device__ __forceinline__ void attn_phase(unsigned char* lds, const Params& p, int jl, const bf16_t* proj, bf16_t* mix, int blk, int G, int tid) {
;     ...
;             if (t >= w_lo && t <= w_hi) {
;                 const bf16_t* ks = KS + buf * (64 * 136); const bf16_t* vt = VT + buf * (128 * 72);
;                 const int nvk = (samp && t == 8) ? 32 : 64;
;                 f32x4 s[2][4];
; #pragma unroll
;                 for (int qt = 0; qt < 2; ++qt)
; #pragma unroll
;                     for (int kt = 0; kt < 4; ++kt) s[qt][kt] = (f32x4){0.f, 0.f, 0.f, 0.f};
; #pragma unroll
;                 for (int kh2 = 0; kh2 < 2; ++kh2) { bf16x8 kf[2][4];
; #pragma unroll
;                     for (int kt = 0; kt < 2; ++kt)
; #pragma unroll
;                         for (int k4 = 0; k4 < 4; ++k4) kf[kt][k4] = *(const bf16x8*)(ks + ((kh2 * 2 + kt) * 16 + fr) * 136 + k4 * 32 + fq * 8);
;                     __builtin_amdgcn_sched_barrier(0);
; #pragma unroll
;                     for (int k4 = 0; k4 < 4; ++k4)
; #pragma unroll
;                         for (int kt = 0; kt < 2; ++kt)
; #pragma unroll
;                             for (int qt = 0; qt < 2; ++qt) s[qt][kh2 * 2 + kt] = MFMA16(kf[kt][k4], qf[qt][k4], s[qt][kh2 * 2 + kt]);
;                     __builtin_amdgcn_sched_barrier(0); }
;                 bf16x8 vf[4][2][2];
;     ...
;                 ATT_VLOAD(0);
;                 __builtin_amdgcn_sched_barrier(0);
;                 bf16x8 pb[2][2];
; #pragma unroll
;                 for (int qt = 0; qt < 2; ++qt) {
;                     const float* bp = BIAS + (575 - (qpos0 + qt * 16 - t * 64 - fq * 4));
; #pragma unroll
;                     for (int kt = 0; kt < 4; ++kt) { const f32x4 bv = {bp[kt * 16], bp[kt * 16 + 1], bp[kt * 16 + 2], bp[kt * 16 + 3]}; s[qt][kt] = s[qt][kt] * SC2 + bv; }
;                     if (nvk < 64) {
; #pragma unroll
;                         for (int kt = 0; kt < 4; ++kt)
; #pragma unroll
;                             for (int j = 0; j < 4; ++j) if (kt * 16 + fq * 4 + j >= nvk) s[qt][kt][j] = NEG_INF; }
;                     float mx;
;                     { const f32x4 m01 = __builtin_elementwise_max(s[qt][0], s[qt][1]), m23 = __builtin_elementwise_max(s[qt][2], s[qt][3]), m4 = __builtin_elementwise_max(m01, m23);
;                       mx = fmaxf(fmaxf(m4[0], m4[1]), fmaxf(m4[2], m4[3])); }
.LBB0_205:
	v_cmp_ge_i32_e32 vcc, s47, v202
	v_cmp_le_i32_e64 s[4:5], s47, v203
	s_and_b32 s20, s35, 1
	s_and_b64 s[4:5], vcc, s[4:5]
	s_and_saveexec_b64 s[18:19], s[4:5]
	s_cbranch_execz .LBB0_211
	s_mul_i32 s4, s20, 0x4400
	v_add_u32_e32 v0, s4, v195
	ds_read_b128 v[116:119], v0
	ds_read_b128 v[120:123], v0 offset:64
	ds_read_b128 v[124:127], v0 offset:128
	ds_read_b128 v[128:131], v0 offset:192
	ds_read_b128 v[132:135], v0 offset:4352
	ds_read_b128 v[136:139], v0 offset:4416
	ds_read_b128 v[140:143], v0 offset:4480
	ds_read_b128 v[144:147], v0 offset:4544
	s_cmp_eq_u32 s47, 8
	s_mul_i32 s21, s20, 0x4800
	s_cselect_b64 s[4:5], -1, 0
	s_and_b64 s[4:5], s[6:7], s[4:5]
	s_add_i32 s21, s21, 0
	s_waitcnt lgkmcnt(7)
	v_mfma_f32_16x16x32_bf16 v[168:171], v[116:119], v[52:55], 0
	v_mfma_f32_16x16x32_bf16 v[116:119], v[116:119], v[76:79], 0
	s_waitcnt lgkmcnt(3)
	v_mfma_f32_16x16x32_bf16 v[172:175], v[132:135], v[52:55], 0
	v_mfma_f32_16x16x32_bf16 v[132:135], v[132:135], v[76:79], 0
	v_mfma_f32_16x16x32_bf16 v[168:171], v[120:123], v[56:59], v[168:171]
	v_mfma_f32_16x16x32_bf16 v[116:119], v[120:123], v[68:71], v[116:119]
	s_waitcnt lgkmcnt(2)
	v_mfma_f32_16x16x32_bf16 v[120:123], v[136:139], v[56:59], v[172:175]
	v_mfma_f32_16x16x32_bf16 v[132:135], v[136:139], v[68:71], v[132:135]
	v_mfma_f32_16x16x32_bf16 v[136:139], v[124:127], v[60:63], v[168:171]
	v_mfma_f32_16x16x32_bf16 v[116:119], v[124:127], v[72:75], v[116:119]
	s_waitcnt lgkmcnt(1)
	v_mfma_f32_16x16x32_bf16 v[120:123], v[140:143], v[60:63], v[120:123]
	v_mfma_f32_16x16x32_bf16 v[124:127], v[140:143], v[72:75], v[132:135]
	v_mfma_f32_16x16x32_bf16 v[170:173], v[128:131], v[64:67], v[136:139]
	v_mfma_f32_16x16x32_bf16 v[132:135], v[128:131], v[80:83], v[116:119]
	s_waitcnt lgkmcnt(0)
	v_mfma_f32_16x16x32_bf16 v[182:185], v[144:147], v[64:67], v[120:123]
	v_mfma_f32_16x16x32_bf16 v[136:139], v[144:147], v[80:83], v[124:127]
	ds_read_b128 v[116:119], v0 offset:8704
	s_nop 0
	ds_read_b128 v[120:123], v0 offset:8768
	ds_read_b128 v[124:127], v0 offset:8832
	ds_read_b128 v[128:131], v0 offset:8896
	ds_read_b128 v[140:143], v0 offset:13056
	ds_read_b128 v[144:147], v0 offset:13120
	ds_read_b128 v[174:177], v0 offset:13184
	ds_read_b128 v[178:181], v0 offset:13248
	s_waitcnt lgkmcnt(7)
	v_mfma_f32_16x16x32_bf16 v[216:219], v[116:119], v[52:55], 0
	v_mfma_f32_16x16x32_bf16 v[116:119], v[116:119], v[76:79], 0
	s_waitcnt lgkmcnt(3)
	v_mfma_f32_16x16x32_bf16 v[220:223], v[140:143], v[52:55], 0
	v_mfma_f32_16x16x32_bf16 v[140:143], v[140:143], v[76:79], 0
	v_mfma_f32_16x16x32_bf16 v[216:219], v[120:123], v[56:59], v[216:219]
	v_mfma_f32_16x16x32_bf16 v[116:119], v[120:123], v[68:71], v[116:119]
	s_waitcnt lgkmcnt(2)
	v_mfma_f32_16x16x32_bf16 v[140:143], v[144:147], v[68:71], v[140:143]
	v_mfma_f32_16x16x32_bf16 v[120:123], v[144:147], v[56:59], v[220:223]
	v_mfma_f32_16x16x32_bf16 v[144:147], v[124:127], v[60:63], v[216:219]
	v_mfma_f32_16x16x32_bf16 v[116:119], v[124:127], v[72:75], v[116:119]
	s_waitcnt lgkmcnt(1)
	v_mfma_f32_16x16x32_bf16 v[124:127], v[174:177], v[72:75], v[140:143]
	v_mfma_f32_16x16x32_bf16 v[120:123], v[174:177], v[60:63], v[120:123]
	v_mfma_f32_16x16x32_bf16 v[222:225], v[128:131], v[64:67], v[144:147]
	v_mfma_f32_16x16x32_bf16 v[144:147], v[128:131], v[80:83], v[116:119]
	s_waitcnt lgkmcnt(0)
	v_mfma_f32_16x16x32_bf16 v[140:143], v[178:181], v[80:83], v[124:127]
	v_mfma_f32_16x16x32_bf16 v[226:229], v[178:181], v[64:67], v[120:123]
	v_add3_u32 v0, s21, v160, v161
	v_add_u32_e32 v2, 0x8800, v0
	v_add_u32_e32 v0, 0x9000, v0
	ds_read_b64 v[124:125], v2
	ds_read_b64 v[126:127], v2 offset:32
	ds_read_b64 v[120:121], v2 offset:64
	ds_read_b64 v[122:123], v2 offset:96
	ds_read_b64 v[128:129], v0 offset:256
	ds_read_b64 v[130:131], v0 offset:288
	ds_read_b64 v[116:117], v0 offset:320
	ds_read_b64 v[118:119], v0 offset:352
	v_and_b32_e32 v2, 64, v213
	ds_read2_b32 v[174:175], v204 offset0:16 offset1:17
	ds_read2_b32 v[176:177], v204 offset0:18 offset1:19
	ds_read2_b32 v[178:179], v204 offset0:32 offset1:33
	ds_read2_b32 v[180:181], v204 offset0:34 offset1:35
	v_xor_b32_e32 v0, 16, v213
	v_add_u32_e32 v2, 64, v2
	v_cmp_lt_i32_e32 vcc, v0, v2
	s_mov_b32 s28, 0x3e0293ee
	s_waitcnt lgkmcnt(2)
	v_pk_fma_f32 v[168:169], v[172:173], s[28:29], v[176:177] op_sel_hi:[1,0,1]
	v_cndmask_b32_e32 v0, v213, v0, vcc
	v_lshlrev_b32_e32 v219, 2, v0
	v_xor_b32_e32 v0, 32, v213
	v_cmp_lt_i32_e32 vcc, v0, v2
	v_pk_fma_f32 v[2:3], v[170:171], s[28:29], v[174:175] op_sel_hi:[1,0,1]
	s_waitcnt lgkmcnt(0)
	v_pk_fma_f32 v[172:173], v[184:185], s[28:29], v[180:181] op_sel_hi:[1,0,1]
	v_pk_fma_f32 v[170:171], v[182:183], s[28:29], v[178:179] op_sel_hi:[1,0,1]
	ds_read2_b32 v[182:183], v204 offset0:48 offset1:49
	ds_read2_b32 v[184:185], v204 offset0:50 offset1:51
	ds_read2_b32 v[210:211], v204 offset0:64 offset1:65
	ds_read2_b32 v[216:217], v204 offset0:66 offset1:67
	v_cndmask_b32_e32 v0, v213, v0, vcc
	v_lshlrev_b32_e32 v220, 2, v0
	s_waitcnt lgkmcnt(3)
	v_pk_fma_f32 v[188:189], v[222:223], s[28:29], v[182:183] op_sel_hi:[1,0,1]
	s_waitcnt lgkmcnt(2)
	v_pk_fma_f32 v[152:153], v[224:225], s[28:29], v[184:185] op_sel_hi:[1,0,1]
	s_waitcnt lgkmcnt(0)
	v_pk_fma_f32 v[216:217], v[228:229], s[28:29], v[216:217] op_sel_hi:[1,0,1]
	v_cndmask_b32_e64 v222, v152, v214, s[4:5]
	v_cndmask_b32_e64 v216, v216, v214, s[4:5]
	v_pk_fma_f32 v[210:211], v[226:227], s[28:29], v[210:211] op_sel_hi:[1,0,1]
	v_cndmask_b32_e64 v215, v217, v214, s[4:5]
	v_cndmask_b32_e64 v221, v153, v214, s[4:5]
	v_cndmask_b32_e64 v218, v210, v214, s[4:5]
	v_cndmask_b32_e64 v224, v188, v214, s[4:5]
	v_cndmask_b32_e64 v217, v211, v214, s[4:5]
	v_cndmask_b32_e64 v223, v189, v214, s[4:5]
	v_max_f32_e32 v0, v222, v216
	v_max_f32_e32 v152, v221, v215
	v_max_f32_e32 v153, v224, v218
	v_max_f32_e32 v187, v223, v217
	v_max3_f32 v152, v169, v173, v152
	v_max3_f32 v0, v168, v172, v0
	v_max3_f32 v187, v3, v171, v187
	v_max3_f32 v153, v2, v170, v153
	v_max_f32_e32 v0, v0, v152
	v_max3_f32 v0, v153, v187, v0
	ds_bpermute_b32 v152, v219, v0
	s_waitcnt lgkmcnt(0)
	v_max_f32_e32 v0, v0, v152
	ds_bpermute_b32 v152, v220, v0
	s_waitcnt lgkmcnt(0)
	v_max_f32_e32 v0, v0, v152
	v_sub_f32_e32 v152, v0, v186
	v_cmp_lt_f32_e32 vcc, 4.0, v152
	s_nop 1
	v_cndmask_b32_e32 v207, v186, v0, vcc
	v_sub_f32_e32 v0, v186, v207
	v_exp_f32_e32 v0, v0
	s_nop 0
	v_cmp_neq_f32_e32 vcc, 1.0, v0
	s_cbranch_vccz .LBB0_208
; __device__ __forceinline__ void attn_phase(unsigned char* lds, const Params& p, int jl, const bf16_t* proj, bf16_t* mix, int blk, int G, int tid) {
;     ...
;                     const float* bp = BIAS + (575 - (qpos0 + qt * 16 - t * 64 - fq * 4));
; #pragma unroll
;                     for (int kt = 0; kt < 4; ++kt) { const f32x4 bv = {bp[kt * 16], bp[kt * 16 + 1], bp[kt * 16 + 2], bp[kt * 16 + 3]}; s[qt][kt] = s[qt][kt] * SC2 + bv; }
;                     if (nvk < 64) {
; #pragma unroll
;                         for (int kt = 0; kt < 4; ++kt)
; #pragma unroll
;                             for (int j = 0; j < 4; ++j) if (kt * 16 + fq * 4 + j >= nvk) s[qt][kt][j] = NEG_INF; }
;                     float mx;
;                     { const f32x4 m01 = __builtin_elementwise_max(s[qt][0], s[qt][1]), m23 = __builtin_elementwise_max(s[qt][2], s[qt][3]), m4 = __builtin_elementwise_max(m01, m23);
;                       mx = fmaxf(fmaxf(m4[0], m4[1]), fmaxf(m4[2], m4[3])); }
;                     mx = fmaxf(mx, __shfl_xor(mx, 16)); mx = fmaxf(mx, __shfl_xor(mx, 32));
;                     const float m_new = fmaxf(m_run[qt], mx), alpha = __builtin_amdgcn_exp2f(m_run[qt] - m_new);
; #pragma unroll
;                     for (int kt = 0; kt < 4; ++kt) { s[qt][kt] = s[qt][kt] - m_new;
; #pragma unroll
;                         for (int j = 0; j < 4; ++j) s[qt][kt][j] = __builtin_amdgcn_exp2f(s[qt][kt][j]); }
;                     const f32x4 sv4 = (s[qt][0] + s[qt][1]) + (s[qt][2] + s[qt][3]);
;                     const float ps = (sv4[0] + sv4[1]) + (sv4[2] + sv4[3]);
;                     l_run[qt] = l_run[qt] * alpha + ps; m_run[qt] = m_new;
;                     if (__any(alpha != 1.f)) {
; #pragma unroll
;                         for (int dt = 0; dt < 8; ++dt) o[qt][dt] = o[qt][dt] * alpha; }
	v_pk_mul_f32 v[106:107], v[106:107], v[0:1] op_sel_hi:[1,0]
	v_pk_mul_f32 v[104:105], v[104:105], v[0:1] op_sel_hi:[1,0]
	v_pk_mul_f32 v[98:99], v[98:99], v[0:1] op_sel_hi:[1,0]
	v_pk_mul_f32 v[96:97], v[96:97], v[0:1] op_sel_hi:[1,0]
	v_pk_mul_f32 v[90:91], v[90:91], v[0:1] op_sel_hi:[1,0]
	v_pk_mul_f32 v[88:89], v[88:89], v[0:1] op_sel_hi:[1,0]
	v_pk_mul_f32 v[86:87], v[86:87], v[0:1] op_sel_hi:[1,0]
	v_pk_mul_f32 v[84:85], v[84:85], v[0:1] op_sel_hi:[1,0]
	v_pk_mul_f32 v[50:51], v[50:51], v[0:1] op_sel_hi:[1,0]
	v_pk_mul_f32 v[48:49], v[48:49], v[0:1] op_sel_hi:[1,0]
	v_pk_mul_f32 v[46:47], v[46:47], v[0:1] op_sel_hi:[1,0]
	v_pk_mul_f32 v[44:45], v[44:45], v[0:1] op_sel_hi:[1,0]
	v_pk_mul_f32 v[42:43], v[42:43], v[0:1] op_sel_hi:[1,0]
	v_pk_mul_f32 v[40:41], v[40:41], v[0:1] op_sel_hi:[1,0]
	v_pk_mul_f32 v[38:39], v[38:39], v[0:1] op_sel_hi:[1,0]
	v_pk_mul_f32 v[36:37], v[36:37], v[0:1] op_sel_hi:[1,0]
.LBB0_208:
	ds_read2_b32 v[152:153], v204 offset0:2 offset1:3
	ds_read2_b32 v[186:187], v204 offset1:1
	v_pk_fma_f32 v[174:175], v[136:137], s[28:29], v[174:175] op_sel_hi:[1,0,1]
	v_pk_fma_f32 v[136:137], v[142:143], s[28:29], v[184:185] op_sel_hi:[1,0,1]
	v_pk_fma_f32 v[176:177], v[138:139], s[28:29], v[176:177] op_sel_hi:[1,0,1]
	v_cndmask_b32_e64 v143, v136, v214, s[4:5]
	s_waitcnt lgkmcnt(0)
	v_pk_fma_f32 v[186:187], v[132:133], s[28:29], v[186:187] op_sel_hi:[1,0,1]
	v_pk_fma_f32 v[132:133], v[146:147], s[28:29], v[180:181] op_sel_hi:[1,0,1]
	v_pk_fma_f32 v[188:189], v[134:135], s[28:29], v[152:153] op_sel_hi:[1,0,1]
	v_cndmask_b32_e64 v147, v132, v214, s[4:5]
	v_pk_fma_f32 v[134:135], v[144:145], s[28:29], v[178:179] op_sel_hi:[1,0,1]
	v_pk_fma_f32 v[138:139], v[140:141], s[28:29], v[182:183] op_sel_hi:[1,0,1]
	v_cndmask_b32_e64 v142, v137, v214, s[4:5]
	v_cndmask_b32_e64 v146, v133, v214, s[4:5]
	v_cndmask_b32_e64 v145, v138, v214, s[4:5]
	v_cndmask_b32_e64 v179, v134, v214, s[4:5]
	v_cndmask_b32_e64 v144, v139, v214, s[4:5]
	v_cndmask_b32_e64 v178, v135, v214, s[4:5]
	v_max_f32_e32 v132, v147, v143
	v_max_f32_e32 v133, v146, v142
	v_max_f32_e32 v134, v179, v145
	v_max_f32_e32 v135, v178, v144
	v_max3_f32 v133, v189, v177, v133
	v_max3_f32 v132, v188, v176, v132
	v_max3_f32 v135, v187, v175, v135
	v_max3_f32 v134, v186, v174, v134
	v_max_f32_e32 v132, v132, v133
	v_max3_f32 v132, v134, v135, v132
	ds_bpermute_b32 v133, v219, v132
	s_waitcnt lgkmcnt(0)
	v_max_f32_e32 v132, v132, v133
	ds_bpermute_b32 v133, v220, v132
	s_waitcnt lgkmcnt(0)
	v_max_f32_e32 v132, v132, v133
	v_sub_f32_e32 v133, v132, v206
	v_cmp_lt_f32_e32 vcc, 4.0, v133
	s_nop 1
	v_cndmask_b32_e32 v141, v206, v132, vcc
	v_sub_f32_e32 v132, v206, v141
	v_exp_f32_e32 v140, v132
	s_nop 0
	v_cmp_neq_f32_e32 vcc, 1.0, v140
	s_cbranch_vccz .LBB0_210
	v_pk_mul_f32 v[34:35], v[34:35], v[140:141] op_sel_hi:[1,0]
	v_pk_mul_f32 v[32:33], v[32:33], v[140:141] op_sel_hi:[1,0]
	v_pk_mul_f32 v[30:31], v[30:31], v[140:141] op_sel_hi:[1,0]
	v_pk_mul_f32 v[28:29], v[28:29], v[140:141] op_sel_hi:[1,0]
	v_pk_mul_f32 v[26:27], v[26:27], v[140:141] op_sel_hi:[1,0]
	v_pk_mul_f32 v[24:25], v[24:25], v[140:141] op_sel_hi:[1,0]
	v_pk_mul_f32 v[22:23], v[22:23], v[140:141] op_sel_hi:[1,0]
	v_pk_mul_f32 v[20:21], v[20:21], v[140:141] op_sel_hi:[1,0]
	v_pk_mul_f32 v[18:19], v[18:19], v[140:141] op_sel_hi:[1,0]
	v_pk_mul_f32 v[16:17], v[16:17], v[140:141] op_sel_hi:[1,0]
	v_pk_mul_f32 v[14:15], v[14:15], v[140:141] op_sel_hi:[1,0]
	v_pk_mul_f32 v[12:13], v[12:13], v[140:141] op_sel_hi:[1,0]
	v_pk_mul_f32 v[10:11], v[10:11], v[140:141] op_sel_hi:[1,0]
	v_pk_mul_f32 v[8:9], v[8:9], v[140:141] op_sel_hi:[1,0]
	v_pk_mul_f32 v[6:7], v[6:7], v[140:141] op_sel_hi:[1,0]
	v_pk_mul_f32 v[4:5], v[4:5], v[140:141] op_sel_hi:[1,0]
.LBB0_210:
	v_sub_f32_e32 v133, v168, v207
	v_exp_f32_e32 v152, v133
	v_sub_f32_e32 v133, v172, v207
	v_sub_f32_e32 v134, v171, v207
	v_sub_f32_e32 v132, v169, v207
	v_sub_f32_e32 v135, v170, v207
	v_exp_f32_e32 v169, v134
	v_exp_f32_e32 v170, v133
	v_sub_f32_e32 v133, v222, v207
	v_sub_f32_e32 v134, v223, v207
	v_sub_f32_e32 v189, v189, v141
	v_sub_f32_e32 v188, v188, v141
	v_sub_f32_e32 v187, v187, v141
	v_sub_f32_e32 v186, v186, v141
	v_sub_f32_e32 v177, v177, v141
	v_sub_f32_e32 v176, v176, v141
	v_sub_f32_e32 v175, v175, v141
	v_sub_f32_e32 v174, v174, v141
	v_sub_f32_e32 v206, v146, v141
	v_sub_f32_e32 v210, v147, v141
	v_sub_f32_e32 v147, v178, v141
	v_sub_f32_e32 v146, v179, v141
	v_sub_f32_e32 v142, v142, v141
	v_sub_f32_e32 v143, v143, v141
	v_sub_f32_e32 v144, v144, v141
	v_sub_f32_e32 v145, v145, v141
	v_exp_f32_e32 v153, v132
	v_sub_f32_e32 v132, v173, v207
	v_exp_f32_e32 v173, v134
	v_exp_f32_e32 v180, v133
	v_sub_f32_e32 v133, v216, v207
	v_sub_f32_e32 v134, v217, v207
	v_exp_f32_e32 v186, v186
	v_exp_f32_e32 v187, v187
	v_exp_f32_e32 v188, v188
	v_exp_f32_e32 v189, v189
	v_exp_f32_e32 v174, v174
	v_exp_f32_e32 v175, v175
	v_exp_f32_e32 v176, v176
	v_exp_f32_e32 v177, v177
	v_exp_f32_e32 v146, v146
	v_exp_f32_e32 v147, v147
	v_exp_f32_e32 v178, v210
	v_exp_f32_e32 v179, v206
	v_exp_f32_e32 v210, v145
	v_exp_f32_e32 v211, v144
	v_exp_f32_e32 v216, v143
	v_exp_f32_e32 v217, v142
	v_exp_f32_e32 v168, v135
	v_exp_f32_e32 v171, v132
	v_sub_f32_e32 v132, v221, v207
	v_sub_f32_e32 v135, v224, v207
	v_sub_f32_e32 v3, v3, v207
	v_sub_f32_e32 v2, v2, v207
	v_exp_f32_e32 v172, v135
	v_exp_f32_e32 v181, v132
	v_sub_f32_e32 v132, v215, v207
	v_sub_f32_e32 v135, v218, v207
	v_exp_f32_e32 v2, v2
	v_exp_f32_e32 v3, v3
	v_exp_f32_e32 v182, v135
	v_exp_f32_e32 v183, v134
	v_exp_f32_e32 v184, v133
	v_exp_f32_e32 v185, v132
	v_pk_add_f32 v[142:143], v[186:187], v[174:175]
; __device__ __forceinline__ bf16x8 pack8(f32x4 a, f32x4 b) { u32x4 w = {pk2(a[0], a[1]), pk2(a[2], a[3]), pk2(b[0], b[1]), pk2(b[2], b[3])}; return __builtin_bit_cast(bf16x8, w); }
; #define ATT_VLOAD(g4) do { _Pragma("unroll") for (int d = 0; d < 2; ++d) _Pragma("unroll") for (int k2 = 0; k2 < 2; ++k2) { const bf16_t* vp = vt + (((g4) * 2 + d) * 16 + fr) * 72 + k2 * 32 + fq * 4; \
;                     vf[g4][d][k2] = cat8(*(const bf16x4*)vp, *(const bf16x4*)(vp + 16)); } } while (0)
; #define ATT_VMMA(g4) do { _Pragma("unroll") for (int k2 = 0; k2 < 2; ++k2) _Pragma("unroll") for (int d = 0; d < 2; ++d) _Pragma("unroll") for (int qt = 0; qt < 2; ++qt) \
;                     o[qt][(g4) * 2 + d] = MFMA16(vf[g4][d][k2], pb[qt][k2], o[qt][(g4) * 2 + d]); } while (0)
; __device__ __forceinline__ void attn_phase(unsigned char* lds, const Params& p, int jl, const bf16_t* proj, bf16_t* mix, int blk, int G, int tid) {
;     ...
;                     const f32x4 sv4 = (s[qt][0] + s[qt][1]) + (s[qt][2] + s[qt][3]);
;                     const float ps = (sv4[0] + sv4[1]) + (sv4[2] + sv4[3]);
;                     l_run[qt] = l_run[qt] * alpha + ps; m_run[qt] = m_new;
;                     if (__any(alpha != 1.f)) {
; #pragma unroll
;                         for (int dt = 0; dt < 8; ++dt) o[qt][dt] = o[qt][dt] * alpha; }
;                     pb[qt][0] = pack8(s[qt][0], s[qt][1]); pb[qt][1] = pack8(s[qt][2], s[qt][3]);
;                 }
;                 __builtin_amdgcn_sched_barrier(0);
;                 ATT_VLOAD(1); ATT_VMMA(0);
;                 __builtin_amdgcn_sched_barrier(0);
;                 ATT_VLOAD(2); ATT_VMMA(1);
;                 __builtin_amdgcn_sched_barrier(0);
;                 ATT_VLOAD(3); ATT_VMMA(2);
;                 __builtin_amdgcn_sched_barrier(0);
;                 ATT_VMMA(3);
	v_pk_add_f32 v[144:145], v[188:189], v[176:177]
	v_pk_add_f32 v[218:219], v[146:147], v[210:211]
	v_pk_add_f32 v[220:221], v[178:179], v[216:217]
	v_pk_add_f32 v[142:143], v[142:143], v[218:219]
	v_pk_add_f32 v[144:145], v[144:145], v[220:221]
	v_add_f32_e32 v142, v142, v143
	v_add_f32_e32 v143, v144, v145
	v_cvt_pk_bf16_f32 v132, v2, v3
	v_cvt_pk_bf16_f32 v133, v152, v153
	v_add_f32_e32 v215, v142, v143
	v_pk_add_f32 v[2:3], v[2:3], v[168:169]
	v_pk_add_f32 v[142:143], v[152:153], v[170:171]
	v_pk_add_f32 v[144:145], v[172:173], v[182:183]
	v_pk_add_f32 v[152:153], v[180:181], v[184:185]
	v_pk_add_f32 v[2:3], v[2:3], v[144:145]
	v_pk_add_f32 v[142:143], v[142:143], v[152:153]
	v_add_f32_e32 v2, v2, v3
	v_add_f32_e32 v3, v142, v143
	v_fmac_f32_e32 v215, v201, v140
	v_add_f32_e32 v140, v2, v3
	v_cvt_pk_bf16_f32 v134, v168, v169
	v_cvt_pk_bf16_f32 v135, v170, v171
	v_cvt_pk_bf16_f32 v136, v172, v173
	v_cvt_pk_bf16_f32 v137, v180, v181
	v_cvt_pk_bf16_f32 v138, v182, v183
	v_cvt_pk_bf16_f32 v139, v184, v185
	v_fmac_f32_e32 v140, v205, v0
	v_cvt_pk_bf16_f32 v142, v186, v187
	v_cvt_pk_bf16_f32 v143, v188, v189
	v_cvt_pk_bf16_f32 v144, v174, v175
	v_cvt_pk_bf16_f32 v145, v176, v177
	v_cvt_pk_bf16_f32 v168, v146, v147
	v_cvt_pk_bf16_f32 v169, v178, v179
	v_cvt_pk_bf16_f32 v170, v210, v211
	v_cvt_pk_bf16_f32 v171, v216, v217
	v_mfma_f32_16x16x32_bf16 v[104:107], v[124:127], v[132:135], v[104:107]
	v_add3_u32 v0, s21, v161, v160
	v_add_u32_e32 v2, 0x9800, v0
	v_mfma_f32_16x16x32_bf16 v[32:35], v[124:127], v[142:145], v[32:35]
	v_mfma_f32_16x16x32_bf16 v[96:99], v[128:131], v[132:135], v[96:99]
	v_mfma_f32_16x16x32_bf16 v[28:31], v[128:131], v[142:145], v[28:31]
	v_mfma_f32_16x16x32_bf16 v[104:107], v[120:123], v[136:139], v[104:107]
	v_mfma_f32_16x16x32_bf16 v[32:35], v[120:123], v[168:171], v[32:35]
	ds_read_b64 v[120:121], v2 offset:512
	ds_read_b64 v[122:123], v2 offset:544
	ds_read_b64 v[124:125], v2 offset:576
	ds_read_b64 v[126:127], v2 offset:608
	v_add_u32_e32 v2, 0xa000, v0
	ds_read_b64 v[128:129], v2 offset:768
	ds_read_b64 v[130:131], v2 offset:800
	ds_read_b64 v[172:173], v2 offset:832
	ds_read_b64 v[174:175], v2 offset:864
	v_mfma_f32_16x16x32_bf16 v[96:99], v[116:119], v[136:139], v[96:99]
	v_mfma_f32_16x16x32_bf16 v[28:31], v[116:119], v[168:171], v[28:31]
	s_waitcnt lgkmcnt(6)
	v_mfma_f32_16x16x32_bf16 v[88:91], v[120:123], v[132:135], v[88:91]
	v_add_u32_e32 v2, 0xa800, v0
	v_mfma_f32_16x16x32_bf16 v[24:27], v[120:123], v[142:145], v[24:27]
	ds_read_b64 v[116:117], v2 offset:1024
	ds_read_b64 v[118:119], v2 offset:1056
	ds_read_b64 v[120:121], v2 offset:1088
	ds_read_b64 v[122:123], v2 offset:1120
	v_add_u32_e32 v2, 0xb000, v0
	s_waitcnt lgkmcnt(6)
	v_mfma_f32_16x16x32_bf16 v[84:87], v[128:131], v[132:135], v[84:87]
	v_mfma_f32_16x16x32_bf16 v[20:23], v[128:131], v[142:145], v[20:23]
	v_mfma_f32_16x16x32_bf16 v[88:91], v[124:127], v[136:139], v[88:91]
	v_mfma_f32_16x16x32_bf16 v[24:27], v[124:127], v[168:171], v[24:27]
	ds_read_b64 v[124:125], v2 offset:1280
	ds_read_b64 v[126:127], v2 offset:1312
	ds_read_b64 v[128:129], v2 offset:1344
	ds_read_b64 v[130:131], v2 offset:1376
	s_waitcnt lgkmcnt(8)
	v_mfma_f32_16x16x32_bf16 v[84:87], v[172:175], v[136:139], v[84:87]
	v_mfma_f32_16x16x32_bf16 v[20:23], v[172:175], v[168:171], v[20:23]
	s_waitcnt lgkmcnt(6)
	v_mfma_f32_16x16x32_bf16 v[48:51], v[116:119], v[132:135], v[48:51]
	v_add_u32_e32 v2, 0xb800, v0
	v_add_u32_e32 v0, 0xc000, v0
	v_mfma_f32_16x16x32_bf16 v[16:19], v[116:119], v[142:145], v[16:19]
	s_waitcnt lgkmcnt(2)
	v_mfma_f32_16x16x32_bf16 v[44:47], v[124:127], v[132:135], v[44:47]
	v_mfma_f32_16x16x32_bf16 v[12:15], v[124:127], v[142:145], v[12:15]
	v_mfma_f32_16x16x32_bf16 v[48:51], v[120:123], v[136:139], v[48:51]
	v_mfma_f32_16x16x32_bf16 v[16:19], v[120:123], v[168:171], v[16:19]
	ds_read_b64 v[116:117], v2 offset:1536
	ds_read_b64 v[118:119], v2 offset:1568
	ds_read_b64 v[120:121], v2 offset:1600
	ds_read_b64 v[122:123], v2 offset:1632
	ds_read_b64 v[124:125], v0 offset:1792
	ds_read_b64 v[126:127], v0 offset:1824
	ds_read_b64 v[172:173], v0 offset:1856
	ds_read_b64 v[174:175], v0 offset:1888
	s_waitcnt lgkmcnt(8)
	v_mfma_f32_16x16x32_bf16 v[44:47], v[128:131], v[136:139], v[44:47]
	v_mfma_f32_16x16x32_bf16 v[12:15], v[128:131], v[168:171], v[12:15]
	s_waitcnt lgkmcnt(6)
	v_mfma_f32_16x16x32_bf16 v[40:43], v[116:119], v[132:135], v[40:43]
	v_mov_b32_e32 v206, v141
	v_mov_b32_e32 v186, v207
	v_mov_b32_e32 v201, v215
	v_mfma_f32_16x16x32_bf16 v[8:11], v[116:119], v[142:145], v[8:11]
	v_mov_b32_e32 v205, v140
	s_waitcnt lgkmcnt(2)
	v_mfma_f32_16x16x32_bf16 v[36:39], v[124:127], v[132:135], v[36:39]
	v_mfma_f32_16x16x32_bf16 v[2:5], v[124:127], v[142:145], v[4:7]
	v_mfma_f32_16x16x32_bf16 v[40:43], v[120:123], v[136:139], v[40:43]
	v_mfma_f32_16x16x32_bf16 v[8:11], v[120:123], v[168:171], v[8:11]
	s_waitcnt lgkmcnt(0)
	v_mfma_f32_16x16x32_bf16 v[36:39], v[172:175], v[136:139], v[36:39]
	v_mfma_f32_16x16x32_bf16 v[4:7], v[172:175], v[168:171], v[2:5]
; __device__ __forceinline__ void attn_phase(unsigned char* lds, const Params& p, int jl, const bf16_t* proj, bf16_t* mix, int blk, int G, int tid) {
;     ...
;             if (i + 1 < nt) ATT_WRITET(buf ^ 1);
.LBB0_211:
	s_or_b64 exec, exec, s[18:19]
	s_andn2_b64 vcc, exec, s[16:17]
	s_cbranch_vccnz .LBB0_180
	v_mov_b32_e32 v0, v158
	s_xor_b32 s4, s20, 1
	s_mul_i32 s5, s4, 0x4400
	v_lshrrev_b32_e32 v2, 4, v0
	s_movk_i32 s16, 0x110
	v_lshlrev_b32_e32 v116, 4, v0
	v_and_b32_e32 v3, 63, v0
	s_add_i32 s5, s5, 0
	v_mul_lo_u32 v2, v2, s16
	v_and_b32_e32 v116, 0xf0, v116
	s_lshl_b32 s4, s4, 10
	v_lshrrev_b32_e32 v0, 3, v0
	v_add3_u32 v2, s5, v2, v116
	s_add_i32 s5, s5, s4
	v_and_b32_e32 v0, 0xffffff8, v0
	s_movk_i32 s4, 0x90
	v_mul_lo_u32 v0, v0, s4
	v_lshlrev_b32_e32 v3, 1, v3
	v_add3_u32 v0, s5, v0, v3
	v_and_b32_e32 v238, 1, v158
	v_mov_b32_e32 v239, 0x1000504
	v_mov_b32_e32 v240, 0x7060302
	v_cmp_eq_u32_e32 vcc, 1, v238
	v_mul_u32_u24_e32 v238, 0x8e, v238
	s_nop 0
	v_cndmask_b32_e32 v241, v239, v240, vcc
	v_add_u32_e32 v0, v0, v238
	s_waitcnt vmcnt(0)
	ds_write_b128 v2, v[92:95]
	ds_write_b128 v2, v[100:103] offset:8704
	v_mov_b32_dpp v230, v108 quad_perm:[1,0,3,2] row_mask:0xf bank_mask:0xf
	v_mov_b32_dpp v231, v112 quad_perm:[1,0,3,2] row_mask:0xf bank_mask:0xf
	v_mov_b32_dpp v232, v109 quad_perm:[1,0,3,2] row_mask:0xf bank_mask:0xf
	v_mov_b32_dpp v233, v113 quad_perm:[1,0,3,2] row_mask:0xf bank_mask:0xf
	v_mov_b32_dpp v234, v110 quad_perm:[1,0,3,2] row_mask:0xf bank_mask:0xf
	v_mov_b32_dpp v235, v114 quad_perm:[1,0,3,2] row_mask:0xf bank_mask:0xf
	v_mov_b32_dpp v236, v111 quad_perm:[1,0,3,2] row_mask:0xf bank_mask:0xf
	v_mov_b32_dpp v237, v115 quad_perm:[1,0,3,2] row_mask:0xf bank_mask:0xf
	v_perm_b32 v230, v108, v230, v241
	v_perm_b32 v231, v112, v231, v241
	v_perm_b32 v232, v109, v232, v241
	v_perm_b32 v233, v113, v233, v241
	v_perm_b32 v234, v110, v234, v241
	v_perm_b32 v235, v114, v235, v241
	v_perm_b32 v236, v111, v236, v241
	v_perm_b32 v237, v115, v237, v241
	ds_write_b32 v0, v230 offset:34816
	ds_write_b32 v0, v231 offset:44032
	ds_write_b32 v0, v232 offset:35104
	ds_write_b32 v0, v233 offset:44320
	ds_write_b32 v0, v234 offset:35392
	ds_write_b32 v0, v235 offset:44608
	ds_write_b32 v0, v236 offset:35680
	ds_write_b32 v0, v237 offset:44896
	s_branch .LBB0_180
